# in-proj GEMM start stagger doubled (two s_sleep 127 for odd in-XCD blocks) on top of v56
# speedup vs baseline: 1.0051x; 1.0035x over previous
.LBB0_968:
	s_andn2_b64 vcc, exec, s[4:5]
	s_cbranch_vccnz .LBB0_1075
	v_readlane_b32 s4, v255, 18
	s_bitcmp0_b32 s4, 3
	v_readlane_b32 s5, v255, 19
	s_cbranch_scc1 .LBB0_971
	s_sleep 0x7f
	s_sleep 0x7f
